# cache hints: merge GEMM gate loads at their last use (g_k at hook k, epilogue gate) are non-temporal so the g_k+1 lines re-read at the next hook can stay in L2; on top of the 4-byte D-loop shift versi
# baseline (speedup 1.0000x reference)
; #define GAS __attribute__((address_space(1)))
; DI float bflo(unsigned u) { return __uint_as_float(u << 16); }
; DI float bfhi(unsigned u) { return __uint_as_float(u & 0xffff0000u); }
; DI float fast_rcp(float x) { return __builtin_amdgcn_rcpf(x); }
;     __device__ __forceinline__ void hook(f32x4 (&acc)[2][2][4][2], const Unit& u, int k, int wr, int wc, int fr, int fq) const {
;         int row0 = u.pm * BM + wr * 64 + fr; int col0 = u.pn * BM + wc * 32 + 8 * fq;
;         asm volatile("" : "+v"(row0), "+v"(col0));
; #pragma unroll
;         for (int ai = 0; ai < 2; ++ai) {
;             u32x4 ga[4][2], gb[4][2];
; #pragma unroll
;             for (int m = 0; m < 4; ++m) { const bf16_t* gp = Gp + (size_t)(row0 + ai * HALF + m * 16) * GW + k * DM + col0;
; #pragma unroll
;                 for (int bj = 0; bj < 2; ++bj) { ga[m][bj] = *(const GAS u32x4*)(gp + bj * HALF); gb[m][bj] = *(const GAS u32x4*)(gp + DM + bj * HALF); } }
; #pragma unroll
;             for (int m = 0; m < 4; ++m)
; #pragma unroll
;                 for (int bj = 0; bj < 2; ++bj) { const u32x4 a = ga[m][bj], b = gb[m][bj];
;                     f32x4 r0, r1;
;                     r0[0] = bflo(a.x) * fast_rcp(bflo(b.x)); r0[1] = bfhi(a.x) * fast_rcp(bfhi(b.x)); r0[2] = bflo(a.y) * fast_rcp(bflo(b.y)); r0[3] = bfhi(a.y) * fast_rcp(bfhi(b.y));
;                     r1[0] = bflo(a.z) * fast_rcp(bflo(b.z)); r1[1] = bfhi(a.z) * fast_rcp(bfhi(b.z)); r1[2] = bflo(a.w) * fast_rcp(bflo(b.w)); r1[3] = bfhi(a.w) * fast_rcp(bfhi(b.w));
;                     acc[ai][bj][m][0] *= r0; acc[ai][bj][m][1] *= r1; }
.LBB0_264:
	s_cmp_eq_u32 s92, 0
	s_cselect_b64 s[34:35], -1, 0
	s_and_b32 s54, s5, 6
	s_cmp_lg_u32 s54, 0
	s_cselect_b64 s[54:55], -1, 0
	s_or_b64 s[34:35], s[34:35], s[54:55]
	s_and_b64 vcc, exec, s[34:35]
	s_cbranch_vccnz .LBB0_263
	v_mov_b32_e32 v2, v222
	v_mov_b32_e32 v132, v224
	s_add_u32 s34, s57, s92
	v_ashrrev_i32_e32 v133, 31, v132
	v_ashrrev_i32_e32 v3, 31, v2
	v_lshlrev_b64 v[132:133], 14, v[132:133]
	v_lshl_add_u64 v[2:3], v[2:3], 1, v[132:133]
	s_addc_u32 s35, s49, s93
	v_lshl_add_u64 v[2:3], s[34:35], 0, v[2:3]
	s_mov_b32 s34, 0x204ff000
	v_add_co_u32_e32 v132, vcc, s34, v2
	s_mov_b32 s34, 0x20500000
	s_nop 0
	v_addc_co_u32_e32 v133, vcc, 0, v3, vcc
	v_add_co_u32_e32 v134, vcc, s34, v2
	s_mov_b32 s34, 0x2053f000
	s_nop 0
	v_addc_co_u32_e32 v135, vcc, 0, v3, vcc
	global_load_dwordx4 v[188:191], v[134:135], off offset:-4096 nt
	global_load_dwordx4 v[192:195], v[134:135], off
	global_load_dwordx4 v[180:183], v[132:133], off offset:256 nt
	global_load_dwordx4 v[184:187], v[134:135], off offset:256
	v_add_co_u32_e32 v132, vcc, s34, v2
	s_mov_b32 s34, 0x20540000
	s_nop 0
	v_addc_co_u32_e32 v133, vcc, 0, v3, vcc
	v_add_co_u32_e32 v134, vcc, s34, v2
	s_mov_b32 s34, 0x2057f000
	s_nop 0
	v_addc_co_u32_e32 v135, vcc, 0, v3, vcc
	global_load_dwordx4 v[172:175], v[134:135], off offset:-4096 nt
	global_load_dwordx4 v[176:179], v[134:135], off
	global_load_dwordx4 v[164:167], v[132:133], off offset:256 nt
	global_load_dwordx4 v[168:171], v[134:135], off offset:256
	v_add_co_u32_e32 v132, vcc, s34, v2
	s_mov_b32 s34, 0x20580000
	s_nop 0
	v_addc_co_u32_e32 v133, vcc, 0, v3, vcc
	v_add_co_u32_e32 v134, vcc, s34, v2
	s_mov_b32 s34, 0x205bf000
	s_nop 0
	v_addc_co_u32_e32 v135, vcc, 0, v3, vcc
	global_load_dwordx4 v[156:159], v[134:135], off offset:-4096 nt
	global_load_dwordx4 v[160:163], v[134:135], off
	global_load_dwordx4 v[136:139], v[132:133], off offset:256 nt
	global_load_dwordx4 v[140:143], v[134:135], off offset:256
	v_add_co_u32_e32 v132, vcc, s34, v2
	s_mov_b32 s34, 0x205c0000
	s_nop 0
	v_addc_co_u32_e32 v133, vcc, 0, v3, vcc
	v_add_co_u32_e32 v144, vcc, s34, v2
	s_mov_b32 s34, 0x206ff000
	s_nop 0
	v_addc_co_u32_e32 v145, vcc, 0, v3, vcc
	global_load_dwordx4 v[148:151], v[144:145], off offset:-4096 nt
	global_load_dwordx4 v[152:155], v[144:145], off
	s_nop 0
	global_load_dwordx4 v[132:135], v[132:133], off offset:256 nt
	s_nop 0
	global_load_dwordx4 v[144:147], v[144:145], off offset:256
	s_waitcnt vmcnt(15)
	v_lshlrev_b32_e32 v242, 16, v188
	s_waitcnt vmcnt(14)
	v_lshlrev_b32_e32 v0, 16, v192
	v_rcp_f32_e32 v240, v0
	v_and_b32_e32 v0, 0xffff0000, v192
	v_rcp_f32_e32 v241, v0
	v_lshlrev_b32_e32 v0, 16, v193
	v_rcp_f32_e32 v192, v0
	v_and_b32_e32 v0, 0xffff0000, v193
	v_rcp_f32_e32 v193, v0
	v_and_b32_e32 v243, 0xffff0000, v188
	v_lshlrev_b32_e32 v188, 16, v189
	v_and_b32_e32 v189, 0xffff0000, v189
	v_lshlrev_b32_e32 v0, 16, v194
	v_pk_mul_f32 v[188:189], v[192:193], v[188:189]
	v_rcp_f32_e32 v192, v0
	v_and_b32_e32 v0, 0xffff0000, v194
	v_rcp_f32_e32 v193, v0
	v_lshlrev_b32_e32 v0, 16, v195
	v_rcp_f32_e32 v194, v0
	v_and_b32_e32 v0, 0xffff0000, v195
	v_rcp_f32_e32 v195, v0
	s_waitcnt vmcnt(12)
	v_lshlrev_b32_e32 v0, 16, v184
	v_pk_mul_f32 v[130:131], v[130:131], v[188:189]
	v_rcp_f32_e32 v188, v0
	v_and_b32_e32 v0, 0xffff0000, v184
	v_rcp_f32_e32 v189, v0
	v_lshlrev_b32_e32 v0, 16, v185
	v_rcp_f32_e32 v184, v0
	v_and_b32_e32 v0, 0xffff0000, v185
	v_rcp_f32_e32 v185, v0
	v_pk_mul_f32 v[240:241], v[240:241], v[242:243]
	v_lshlrev_b32_e32 v242, 16, v190
	v_and_b32_e32 v243, 0xffff0000, v190
	v_lshlrev_b32_e32 v190, 16, v191
	v_and_b32_e32 v191, 0xffff0000, v191
	v_pk_mul_f32 v[190:191], v[194:195], v[190:191]
	v_lshlrev_b32_e32 v0, 16, v186
	v_pk_mul_f32 v[126:127], v[126:127], v[190:191]
	v_lshlrev_b32_e32 v190, 16, v180
	v_and_b32_e32 v191, 0xffff0000, v180
	v_lshlrev_b32_e32 v180, 16, v181
	v_and_b32_e32 v181, 0xffff0000, v181
	v_pk_mul_f32 v[180:181], v[184:185], v[180:181]
	v_rcp_f32_e32 v184, v0
	v_and_b32_e32 v0, 0xffff0000, v186
	v_rcp_f32_e32 v185, v0
	v_lshlrev_b32_e32 v0, 16, v187
	v_rcp_f32_e32 v186, v0
	v_and_b32_e32 v0, 0xffff0000, v187
	v_rcp_f32_e32 v187, v0
	s_waitcnt vmcnt(10)
	v_lshlrev_b32_e32 v0, 16, v176
	v_pk_mul_f32 v[122:123], v[122:123], v[180:181]
	v_rcp_f32_e32 v180, v0
	v_and_b32_e32 v0, 0xffff0000, v176
	v_rcp_f32_e32 v181, v0
	v_lshlrev_b32_e32 v0, 16, v177
	v_rcp_f32_e32 v176, v0
	v_and_b32_e32 v0, 0xffff0000, v177
	v_rcp_f32_e32 v177, v0
	v_pk_mul_f32 v[188:189], v[188:189], v[190:191]
	v_lshlrev_b32_e32 v190, 16, v182
	v_and_b32_e32 v191, 0xffff0000, v182
	v_lshlrev_b32_e32 v182, 16, v183
	v_and_b32_e32 v183, 0xffff0000, v183
	v_pk_mul_f32 v[182:183], v[186:187], v[182:183]
	v_lshlrev_b32_e32 v0, 16, v178
	v_pk_mul_f32 v[118:119], v[118:119], v[182:183]
	v_lshlrev_b32_e32 v182, 16, v172
	v_and_b32_e32 v183, 0xffff0000, v172
	v_lshlrev_b32_e32 v172, 16, v173
	v_and_b32_e32 v173, 0xffff0000, v173
	v_pk_mul_f32 v[172:173], v[176:177], v[172:173]
	v_rcp_f32_e32 v176, v0
	v_and_b32_e32 v0, 0xffff0000, v178
	v_rcp_f32_e32 v177, v0
	v_lshlrev_b32_e32 v0, 16, v179
	v_rcp_f32_e32 v178, v0
	v_and_b32_e32 v0, 0xffff0000, v179
	v_rcp_f32_e32 v179, v0
	s_waitcnt vmcnt(8)
; DI float bflo(unsigned u) { return __uint_as_float(u << 16); }
; DI float bfhi(unsigned u) { return __uint_as_float(u & 0xffff0000u); }
; DI float fast_rcp(float x) { return __builtin_amdgcn_rcpf(x); }
;     __device__ __forceinline__ void hook(f32x4 (&acc)[2][2][4][2], const Unit& u, int k, int wr, int wc, int fr, int fq) const {
;     ...
;                 for (int bj = 0; bj < 2; ++bj) { const u32x4 a = ga[m][bj], b = gb[m][bj];
;                     f32x4 r0, r1;
;                     r0[0] = bflo(a.x) * fast_rcp(bflo(b.x)); r0[1] = bfhi(a.x) * fast_rcp(bfhi(b.x)); r0[2] = bflo(a.y) * fast_rcp(bflo(b.y)); r0[3] = bfhi(a.y) * fast_rcp(bfhi(b.y));
;                     r1[0] = bflo(a.z) * fast_rcp(bflo(b.z)); r1[1] = bfhi(a.z) * fast_rcp(bfhi(b.z)); r1[2] = bflo(a.w) * fast_rcp(bflo(b.w)); r1[3] = bfhi(a.w) * fast_rcp(bfhi(b.w));
;                     acc[ai][bj][m][0] *= r0; acc[ai][bj][m][1] *= r1; }
	v_lshlrev_b32_e32 v0, 16, v168
	v_pk_mul_f32 v[114:115], v[114:115], v[172:173]
	v_rcp_f32_e32 v172, v0
	v_and_b32_e32 v0, 0xffff0000, v168
	v_rcp_f32_e32 v173, v0
	v_lshlrev_b32_e32 v0, 16, v169
	v_rcp_f32_e32 v168, v0
	v_and_b32_e32 v0, 0xffff0000, v169
	v_rcp_f32_e32 v169, v0
	v_pk_mul_f32 v[180:181], v[180:181], v[182:183]
	v_lshlrev_b32_e32 v182, 16, v174
	v_and_b32_e32 v183, 0xffff0000, v174
	v_lshlrev_b32_e32 v174, 16, v175
	v_and_b32_e32 v175, 0xffff0000, v175
	v_pk_mul_f32 v[174:175], v[178:179], v[174:175]
	v_lshlrev_b32_e32 v0, 16, v170
	v_pk_mul_f32 v[110:111], v[110:111], v[174:175]
	v_lshlrev_b32_e32 v174, 16, v164
	v_and_b32_e32 v175, 0xffff0000, v164
	v_lshlrev_b32_e32 v164, 16, v165
	v_and_b32_e32 v165, 0xffff0000, v165
	v_pk_mul_f32 v[164:165], v[168:169], v[164:165]
	v_rcp_f32_e32 v168, v0
	v_and_b32_e32 v0, 0xffff0000, v170
	v_rcp_f32_e32 v169, v0
	v_lshlrev_b32_e32 v0, 16, v171
	v_rcp_f32_e32 v170, v0
	v_and_b32_e32 v0, 0xffff0000, v171
	v_rcp_f32_e32 v171, v0
	s_waitcnt vmcnt(6)
	v_lshlrev_b32_e32 v0, 16, v160
	v_pk_mul_f32 v[106:107], v[106:107], v[164:165]
	v_rcp_f32_e32 v164, v0
	v_and_b32_e32 v0, 0xffff0000, v160
	v_rcp_f32_e32 v165, v0
	v_lshlrev_b32_e32 v0, 16, v161
	v_rcp_f32_e32 v160, v0
	v_and_b32_e32 v0, 0xffff0000, v161
	v_rcp_f32_e32 v161, v0
	v_pk_mul_f32 v[172:173], v[172:173], v[174:175]
	v_lshlrev_b32_e32 v174, 16, v166
	v_and_b32_e32 v175, 0xffff0000, v166
	v_lshlrev_b32_e32 v166, 16, v167
	v_and_b32_e32 v167, 0xffff0000, v167
	v_pk_mul_f32 v[166:167], v[170:171], v[166:167]
	v_lshlrev_b32_e32 v0, 16, v162
	v_pk_mul_f32 v[102:103], v[102:103], v[166:167]
	v_lshlrev_b32_e32 v166, 16, v156
	v_and_b32_e32 v167, 0xffff0000, v156
	v_lshlrev_b32_e32 v156, 16, v157
	v_and_b32_e32 v157, 0xffff0000, v157
	v_pk_mul_f32 v[156:157], v[160:161], v[156:157]
	v_rcp_f32_e32 v160, v0
	v_and_b32_e32 v0, 0xffff0000, v162
	v_rcp_f32_e32 v161, v0
	v_lshlrev_b32_e32 v0, 16, v163
	v_rcp_f32_e32 v162, v0
	v_and_b32_e32 v0, 0xffff0000, v163
	v_rcp_f32_e32 v163, v0
	s_waitcnt vmcnt(4)
	v_lshlrev_b32_e32 v0, 16, v140
	v_pk_mul_f32 v[98:99], v[98:99], v[156:157]
	v_rcp_f32_e32 v156, v0
	v_and_b32_e32 v0, 0xffff0000, v140
	v_rcp_f32_e32 v157, v0
	v_lshlrev_b32_e32 v0, 16, v141
	v_rcp_f32_e32 v140, v0
	v_and_b32_e32 v0, 0xffff0000, v141
	v_rcp_f32_e32 v141, v0
	v_pk_mul_f32 v[164:165], v[164:165], v[166:167]
	v_lshlrev_b32_e32 v166, 16, v158
	v_and_b32_e32 v167, 0xffff0000, v158
	v_lshlrev_b32_e32 v158, 16, v159
	v_and_b32_e32 v159, 0xffff0000, v159
	v_pk_mul_f32 v[158:159], v[162:163], v[158:159]
	v_lshlrev_b32_e32 v0, 16, v142
	v_pk_mul_f32 v[94:95], v[94:95], v[158:159]
	v_lshlrev_b32_e32 v158, 16, v136
	v_and_b32_e32 v159, 0xffff0000, v136
	v_lshlrev_b32_e32 v136, 16, v137
	v_and_b32_e32 v137, 0xffff0000, v137
	v_pk_mul_f32 v[136:137], v[140:141], v[136:137]
	v_rcp_f32_e32 v140, v0
	v_and_b32_e32 v0, 0xffff0000, v142
	v_rcp_f32_e32 v141, v0
	v_lshlrev_b32_e32 v0, 16, v143
	v_rcp_f32_e32 v142, v0
	v_and_b32_e32 v0, 0xffff0000, v143
	v_rcp_f32_e32 v143, v0
	s_waitcnt vmcnt(2)
	v_lshlrev_b32_e32 v0, 16, v152
	v_pk_mul_f32 v[90:91], v[90:91], v[136:137]
	v_rcp_f32_e32 v136, v0
	v_and_b32_e32 v0, 0xffff0000, v152
	v_rcp_f32_e32 v137, v0
	v_pk_mul_f32 v[156:157], v[156:157], v[158:159]
	v_lshlrev_b32_e32 v158, 16, v138
	v_and_b32_e32 v159, 0xffff0000, v138
	v_lshlrev_b32_e32 v138, 16, v139
	v_and_b32_e32 v139, 0xffff0000, v139
	v_pk_mul_f32 v[138:139], v[142:143], v[138:139]
	v_lshlrev_b32_e32 v0, 16, v153
	v_pk_mul_f32 v[86:87], v[86:87], v[138:139]
	v_lshlrev_b32_e32 v138, 16, v148
	v_and_b32_e32 v139, 0xffff0000, v148
	v_pk_mul_f32 v[136:137], v[136:137], v[138:139]
	v_rcp_f32_e32 v138, v0
	v_and_b32_e32 v0, 0xffff0000, v153
	v_rcp_f32_e32 v139, v0
	v_pk_mul_f32 v[140:141], v[140:141], v[158:159]
	v_lshlrev_b32_e32 v0, 16, v154
	v_pk_mul_f32 v[84:85], v[84:85], v[140:141]
	v_lshlrev_b32_e32 v140, 16, v149
	v_and_b32_e32 v141, 0xffff0000, v149
	v_pk_mul_f32 v[138:139], v[138:139], v[140:141]
	v_rcp_f32_e32 v140, v0
	v_and_b32_e32 v0, 0xffff0000, v154
	v_rcp_f32_e32 v141, v0
	v_lshlrev_b32_e32 v142, 16, v150
	v_and_b32_e32 v143, 0xffff0000, v150
	v_lshlrev_b32_e32 v0, 16, v155
	v_pk_mul_f32 v[140:141], v[140:141], v[142:143]
	v_rcp_f32_e32 v142, v0
	v_and_b32_e32 v0, 0xffff0000, v155
	v_rcp_f32_e32 v143, v0
	s_waitcnt vmcnt(0)
; #define GAS __attribute__((address_space(1)))
; DI float bflo(unsigned u) { return __uint_as_float(u << 16); }
; DI float bfhi(unsigned u) { return __uint_as_float(u & 0xffff0000u); }
; DI float fast_rcp(float x) { return __builtin_amdgcn_rcpf(x); }
;     __device__ __forceinline__ void hook(f32x4 (&acc)[2][2][4][2], const Unit& u, int k, int wr, int wc, int fr, int fq) const {
;     ...
;         for (int ai = 0; ai < 2; ++ai) {
;             u32x4 ga[4][2], gb[4][2];
; #pragma unroll
;             for (int m = 0; m < 4; ++m) { const bf16_t* gp = Gp + (size_t)(row0 + ai * HALF + m * 16) * GW + k * DM + col0;
; #pragma unroll
;                 for (int bj = 0; bj < 2; ++bj) { ga[m][bj] = *(const GAS u32x4*)(gp + bj * HALF); gb[m][bj] = *(const GAS u32x4*)(gp + DM + bj * HALF); } }
; #pragma unroll
;             for (int m = 0; m < 4; ++m)
; #pragma unroll
;                 for (int bj = 0; bj < 2; ++bj) { const u32x4 a = ga[m][bj], b = gb[m][bj];
;                     f32x4 r0, r1;
;                     r0[0] = bflo(a.x) * fast_rcp(bflo(b.x)); r0[1] = bfhi(a.x) * fast_rcp(bfhi(b.x)); r0[2] = bflo(a.y) * fast_rcp(bflo(b.y)); r0[3] = bfhi(a.y) * fast_rcp(bfhi(b.y));
;                     r1[0] = bflo(a.z) * fast_rcp(bflo(b.z)); r1[1] = bfhi(a.z) * fast_rcp(bfhi(b.z)); r1[2] = bflo(a.w) * fast_rcp(bflo(b.w)); r1[3] = bfhi(a.w) * fast_rcp(bfhi(b.w));
;                     acc[ai][bj][m][0] *= r0; acc[ai][bj][m][1] *= r1; }
	v_lshlrev_b32_e32 v0, 16, v144
	v_pk_mul_f32 v[80:81], v[80:81], v[136:137]
	v_rcp_f32_e32 v136, v0
	v_and_b32_e32 v0, 0xffff0000, v144
	v_rcp_f32_e32 v137, v0
	v_pk_mul_f32 v[82:83], v[82:83], v[138:139]
	v_lshlrev_b32_e32 v138, 16, v132
	v_and_b32_e32 v139, 0xffff0000, v132
	v_lshlrev_b32_e32 v0, 16, v145
	v_pk_mul_f32 v[136:137], v[136:137], v[138:139]
	v_rcp_f32_e32 v138, v0
	v_and_b32_e32 v0, 0xffff0000, v145
	v_rcp_f32_e32 v139, v0
	v_lshlrev_b32_e32 v132, 16, v133
	v_and_b32_e32 v133, 0xffff0000, v133
	v_lshlrev_b32_e32 v0, 16, v146
	v_pk_mul_f32 v[132:133], v[138:139], v[132:133]
	v_rcp_f32_e32 v138, v0
	v_and_b32_e32 v0, 0xffff0000, v146
	v_rcp_f32_e32 v139, v0
	v_pk_mul_f32 v[76:77], v[76:77], v[140:141]
	v_lshlrev_b32_e32 v140, 16, v134
	v_and_b32_e32 v141, 0xffff0000, v134
	v_lshlrev_b32_e32 v0, 16, v147
	v_pk_mul_f32 v[138:139], v[138:139], v[140:141]
	v_rcp_f32_e32 v140, v0
	v_and_b32_e32 v0, 0xffff0000, v147
	v_rcp_f32_e32 v141, v0
	v_lshlrev_b32_e32 v134, 16, v135
	v_and_b32_e32 v135, 0xffff0000, v135
	v_pk_mul_f32 v[74:75], v[74:75], v[132:133]
	v_add_co_u32_e32 v132, vcc, s34, v2
	v_pk_mul_f32 v[134:135], v[140:141], v[134:135]
	s_nop 0
	v_addc_co_u32_e32 v133, vcc, 0, v3, vcc
	s_mov_b32 s34, 0x20700000
	v_pk_mul_f32 v[70:71], v[70:71], v[134:135]
	v_add_co_u32_e32 v134, vcc, s34, v2
	v_pk_mul_f32 v[192:193], v[192:193], v[242:243]
	v_pk_mul_f32 v[176:177], v[176:177], v[182:183]
	v_addc_co_u32_e32 v135, vcc, 0, v3, vcc
	v_pk_mul_f32 v[124:125], v[124:125], v[192:193]
	v_pk_mul_f32 v[112:113], v[112:113], v[180:181]
	v_pk_mul_f32 v[108:109], v[108:109], v[176:177]
	v_pk_mul_f32 v[160:161], v[160:161], v[166:167]
	v_pk_mul_f32 v[96:97], v[96:97], v[164:165]
	global_load_dwordx4 v[176:179], v[134:135], off offset:-4096 nt
	global_load_dwordx4 v[180:183], v[134:135], off
	global_load_dwordx4 v[164:167], v[132:133], off offset:256 nt
	global_load_dwordx4 v[192:195], v[134:135], off offset:256
	s_mov_b32 s34, 0x2073f000
	v_add_co_u32_e32 v132, vcc, s34, v2
	s_mov_b32 s34, 0x20740000
	s_nop 0
	v_addc_co_u32_e32 v133, vcc, 0, v3, vcc
	v_add_co_u32_e32 v134, vcc, s34, v2
	v_pk_mul_f32 v[184:185], v[184:185], v[190:191]
	v_pk_mul_f32 v[168:169], v[168:169], v[174:175]
	v_addc_co_u32_e32 v135, vcc, 0, v3, vcc
	v_pk_mul_f32 v[120:121], v[120:121], v[188:189]
	v_pk_mul_f32 v[116:117], v[116:117], v[184:185]
	v_pk_mul_f32 v[104:105], v[104:105], v[172:173]
	v_pk_mul_f32 v[100:101], v[100:101], v[168:169]
	global_load_dwordx4 v[184:187], v[134:135], off offset:-4096 nt
	global_load_dwordx4 v[188:191], v[134:135], off
	global_load_dwordx4 v[168:171], v[132:133], off offset:256 nt
	global_load_dwordx4 v[172:175], v[134:135], off offset:256
	s_mov_b32 s34, 0x2077f000
	v_add_co_u32_e32 v132, vcc, s34, v2
	s_mov_b32 s34, 0x20780000
	s_nop 0
	v_addc_co_u32_e32 v133, vcc, 0, v3, vcc
	v_add_co_u32_e32 v134, vcc, s34, v2
	v_lshlrev_b32_e32 v148, 16, v151
	v_and_b32_e32 v149, 0xffff0000, v151
	v_addc_co_u32_e32 v135, vcc, 0, v3, vcc
	v_pk_mul_f32 v[92:93], v[92:93], v[160:161]
	v_pk_mul_f32 v[88:89], v[88:89], v[156:157]
	v_pk_mul_f32 v[142:143], v[142:143], v[148:149]
	global_load_dwordx4 v[156:159], v[134:135], off offset:-4096 nt
	global_load_dwordx4 v[160:163], v[134:135], off
	global_load_dwordx4 v[148:151], v[132:133], off offset:256 nt
	global_load_dwordx4 v[152:155], v[134:135], off offset:256
	s_mov_b32 s34, 0x207bf000
	v_add_co_u32_e32 v132, vcc, s34, v2
	s_mov_b32 s34, 0x207c0000
	s_nop 0
	v_addc_co_u32_e32 v133, vcc, 0, v3, vcc
	v_add_co_u32_e32 v2, vcc, s34, v2
	v_pk_mul_f32 v[78:79], v[78:79], v[142:143]
	s_nop 0
	v_addc_co_u32_e32 v3, vcc, 0, v3, vcc
	v_pk_mul_f32 v[72:73], v[72:73], v[136:137]
	v_pk_mul_f32 v[68:69], v[68:69], v[138:139]
	global_load_dwordx4 v[140:143], v[2:3], off offset:-4096 nt
	global_load_dwordx4 v[144:147], v[2:3], off
	s_nop 0
	global_load_dwordx4 v[132:135], v[132:133], off offset:256 nt
	s_nop 0
	global_load_dwordx4 v[136:139], v[2:3], off offset:256
	v_pk_mul_f32 v[128:129], v[128:129], v[240:241]
	s_waitcnt vmcnt(15)
	v_lshlrev_b32_e32 v240, 16, v176
	s_waitcnt vmcnt(14)
	v_lshlrev_b32_e32 v0, 16, v180
	v_rcp_f32_e32 v2, v0
	v_and_b32_e32 v0, 0xffff0000, v180
	v_rcp_f32_e32 v3, v0
	v_lshlrev_b32_e32 v0, 16, v181
	v_rcp_f32_e32 v180, v0
	v_and_b32_e32 v0, 0xffff0000, v181
	v_rcp_f32_e32 v181, v0
	v_and_b32_e32 v241, 0xffff0000, v176
	v_lshlrev_b32_e32 v176, 16, v177
	v_and_b32_e32 v177, 0xffff0000, v177
	v_lshlrev_b32_e32 v0, 16, v182
	v_pk_mul_f32 v[176:177], v[180:181], v[176:177]
	v_rcp_f32_e32 v180, v0
	v_and_b32_e32 v0, 0xffff0000, v182
	v_rcp_f32_e32 v181, v0
	v_lshlrev_b32_e32 v0, 16, v183
	v_rcp_f32_e32 v182, v0
	v_and_b32_e32 v0, 0xffff0000, v183
	v_pk_mul_f32 v[2:3], v[2:3], v[240:241]
	v_rcp_f32_e32 v183, v0
	s_waitcnt vmcnt(12)
	v_lshlrev_b32_e32 v0, 16, v192
	v_pk_mul_f32 v[64:65], v[64:65], v[2:3]
	v_rcp_f32_e32 v2, v0
	v_and_b32_e32 v0, 0xffff0000, v192
	v_rcp_f32_e32 v3, v0
	v_pk_mul_f32 v[66:67], v[66:67], v[176:177]
	v_lshlrev_b32_e32 v176, 16, v164
	v_and_b32_e32 v177, 0xffff0000, v164
	v_lshlrev_b32_e32 v0, 16, v193
	v_pk_mul_f32 v[2:3], v[2:3], v[176:177]
	v_rcp_f32_e32 v176, v0
	v_and_b32_e32 v0, 0xffff0000, v193
	v_rcp_f32_e32 v177, v0
	v_lshlrev_b32_e32 v164, 16, v165
	v_and_b32_e32 v165, 0xffff0000, v165
	v_lshlrev_b32_e32 v0, 16, v194
	v_pk_mul_f32 v[164:165], v[176:177], v[164:165]
	v_rcp_f32_e32 v176, v0
	v_and_b32_e32 v0, 0xffff0000, v194
	v_rcp_f32_e32 v177, v0
	v_lshlrev_b32_e32 v240, 16, v178
	v_and_b32_e32 v241, 0xffff0000, v178
	v_lshlrev_b32_e32 v178, 16, v179
	v_and_b32_e32 v179, 0xffff0000, v179
	v_pk_mul_f32 v[178:179], v[182:183], v[178:179]
	v_lshlrev_b32_e32 v0, 16, v195
	v_pk_mul_f32 v[62:63], v[62:63], v[178:179]
	v_lshlrev_b32_e32 v178, 16, v166
	v_and_b32_e32 v179, 0xffff0000, v166
	v_pk_mul_f32 v[176:177], v[176:177], v[178:179]
	v_rcp_f32_e32 v178, v0
	v_and_b32_e32 v0, 0xffff0000, v195
	v_rcp_f32_e32 v179, v0
	s_waitcnt vmcnt(10)
; DI float bflo(unsigned u) { return __uint_as_float(u << 16); }
; DI float bfhi(unsigned u) { return __uint_as_float(u & 0xffff0000u); }
; DI float fast_rcp(float x) { return __builtin_amdgcn_rcpf(x); }
;     __device__ __forceinline__ void hook(f32x4 (&acc)[2][2][4][2], const Unit& u, int k, int wr, int wc, int fr, int fq) const {
;     ...
;                 for (int bj = 0; bj < 2; ++bj) { const u32x4 a = ga[m][bj], b = gb[m][bj];
;                     f32x4 r0, r1;
;                     r0[0] = bflo(a.x) * fast_rcp(bflo(b.x)); r0[1] = bfhi(a.x) * fast_rcp(bfhi(b.x)); r0[2] = bflo(a.y) * fast_rcp(bflo(b.y)); r0[3] = bfhi(a.y) * fast_rcp(bfhi(b.y));
;                     r1[0] = bflo(a.z) * fast_rcp(bflo(b.z)); r1[1] = bfhi(a.z) * fast_rcp(bfhi(b.z)); r1[2] = bflo(a.w) * fast_rcp(bflo(b.w)); r1[3] = bfhi(a.w) * fast_rcp(bfhi(b.w));
;                     acc[ai][bj][m][0] *= r0; acc[ai][bj][m][1] *= r1; }
	v_lshlrev_b32_e32 v0, 16, v188
	v_pk_mul_f32 v[56:57], v[56:57], v[2:3]
	v_rcp_f32_e32 v2, v0
	v_and_b32_e32 v0, 0xffff0000, v188
	v_rcp_f32_e32 v3, v0
	v_pk_mul_f32 v[58:59], v[58:59], v[164:165]
	v_lshlrev_b32_e32 v164, 16, v184
	v_and_b32_e32 v165, 0xffff0000, v184
	v_lshlrev_b32_e32 v0, 16, v189
	v_pk_mul_f32 v[2:3], v[2:3], v[164:165]
	v_rcp_f32_e32 v164, v0
	v_and_b32_e32 v0, 0xffff0000, v189
	v_rcp_f32_e32 v165, v0
	v_lshlrev_b32_e32 v166, 16, v167
	v_and_b32_e32 v167, 0xffff0000, v167
	v_pk_mul_f32 v[166:167], v[178:179], v[166:167]
	v_lshlrev_b32_e32 v0, 16, v190
	v_pk_mul_f32 v[54:55], v[54:55], v[166:167]
	v_lshlrev_b32_e32 v166, 16, v185
	v_and_b32_e32 v167, 0xffff0000, v185
	v_pk_mul_f32 v[164:165], v[164:165], v[166:167]
	v_rcp_f32_e32 v166, v0
	v_and_b32_e32 v0, 0xffff0000, v190
	v_rcp_f32_e32 v167, v0
	v_pk_mul_f32 v[52:53], v[52:53], v[176:177]
	v_lshlrev_b32_e32 v176, 16, v186
	v_and_b32_e32 v177, 0xffff0000, v186
	v_lshlrev_b32_e32 v0, 16, v191
	v_pk_mul_f32 v[166:167], v[166:167], v[176:177]
	v_rcp_f32_e32 v176, v0
	v_and_b32_e32 v0, 0xffff0000, v191
	v_rcp_f32_e32 v177, v0
	s_waitcnt vmcnt(8)
	v_lshlrev_b32_e32 v0, 16, v172
	v_pk_mul_f32 v[48:49], v[48:49], v[2:3]
	v_rcp_f32_e32 v2, v0
	v_and_b32_e32 v0, 0xffff0000, v172
	v_rcp_f32_e32 v3, v0
	v_pk_mul_f32 v[50:51], v[50:51], v[164:165]
	v_lshlrev_b32_e32 v164, 16, v168
	v_and_b32_e32 v165, 0xffff0000, v168
	v_lshlrev_b32_e32 v0, 16, v173
	v_pk_mul_f32 v[2:3], v[2:3], v[164:165]
	v_rcp_f32_e32 v164, v0
	v_and_b32_e32 v0, 0xffff0000, v173
	v_rcp_f32_e32 v165, v0
	v_pk_mul_f32 v[44:45], v[44:45], v[166:167]
	v_lshlrev_b32_e32 v166, 16, v169
	v_and_b32_e32 v167, 0xffff0000, v169
	v_lshlrev_b32_e32 v0, 16, v174
	v_pk_mul_f32 v[164:165], v[164:165], v[166:167]
	v_rcp_f32_e32 v166, v0
	v_and_b32_e32 v0, 0xffff0000, v174
	v_rcp_f32_e32 v167, v0
	v_lshlrev_b32_e32 v168, 16, v170
	v_and_b32_e32 v169, 0xffff0000, v170
	v_lshlrev_b32_e32 v0, 16, v175
	v_pk_mul_f32 v[166:167], v[166:167], v[168:169]
	v_rcp_f32_e32 v168, v0
	v_and_b32_e32 v0, 0xffff0000, v175
	v_rcp_f32_e32 v169, v0
	s_waitcnt vmcnt(6)
	v_lshlrev_b32_e32 v0, 16, v160
	v_pk_mul_f32 v[40:41], v[40:41], v[2:3]
	v_rcp_f32_e32 v2, v0
	v_and_b32_e32 v0, 0xffff0000, v160
	v_rcp_f32_e32 v3, v0
	v_lshlrev_b32_e32 v0, 16, v161
	v_rcp_f32_e32 v160, v0
	v_and_b32_e32 v0, 0xffff0000, v161
	v_rcp_f32_e32 v161, v0
	v_pk_mul_f32 v[42:43], v[42:43], v[164:165]
	v_lshlrev_b32_e32 v164, 16, v156
	v_and_b32_e32 v165, 0xffff0000, v156
	v_lshlrev_b32_e32 v156, 16, v157
	v_and_b32_e32 v157, 0xffff0000, v157
	v_lshlrev_b32_e32 v0, 16, v162
	v_pk_mul_f32 v[156:157], v[160:161], v[156:157]
	v_rcp_f32_e32 v160, v0
	v_and_b32_e32 v0, 0xffff0000, v162
	v_rcp_f32_e32 v161, v0
	v_lshlrev_b32_e32 v0, 16, v163
	v_rcp_f32_e32 v162, v0
	v_and_b32_e32 v0, 0xffff0000, v163
	v_pk_mul_f32 v[2:3], v[2:3], v[164:165]
	v_rcp_f32_e32 v163, v0
	s_waitcnt vmcnt(4)
	v_lshlrev_b32_e32 v0, 16, v152
	v_pk_mul_f32 v[32:33], v[32:33], v[2:3]
	v_rcp_f32_e32 v2, v0
	v_and_b32_e32 v0, 0xffff0000, v152
	v_rcp_f32_e32 v3, v0
	v_lshlrev_b32_e32 v0, 16, v153
	v_rcp_f32_e32 v152, v0
	v_and_b32_e32 v0, 0xffff0000, v153
	v_rcp_f32_e32 v153, v0
	v_pk_mul_f32 v[34:35], v[34:35], v[156:157]
	v_lshlrev_b32_e32 v156, 16, v148
	v_and_b32_e32 v157, 0xffff0000, v148
	v_lshlrev_b32_e32 v148, 16, v149
	v_and_b32_e32 v149, 0xffff0000, v149
	v_lshlrev_b32_e32 v0, 16, v154
	v_pk_mul_f32 v[148:149], v[152:153], v[148:149]
	v_rcp_f32_e32 v152, v0
	v_and_b32_e32 v0, 0xffff0000, v154
	v_rcp_f32_e32 v153, v0
	v_lshlrev_b32_e32 v0, 16, v155
	v_rcp_f32_e32 v154, v0
	v_and_b32_e32 v0, 0xffff0000, v155
	v_pk_mul_f32 v[2:3], v[2:3], v[156:157]
	v_rcp_f32_e32 v155, v0
	s_waitcnt vmcnt(2)
; DI float bflo(unsigned u) { return __uint_as_float(u << 16); }
; DI float bfhi(unsigned u) { return __uint_as_float(u & 0xffff0000u); }
; DI float fast_rcp(float x) { return __builtin_amdgcn_rcpf(x); }
;     __device__ __forceinline__ void hook(f32x4 (&acc)[2][2][4][2], const Unit& u, int k, int wr, int wc, int fr, int fq) const {
;     ...
;                 for (int bj = 0; bj < 2; ++bj) { const u32x4 a = ga[m][bj], b = gb[m][bj];
;                     f32x4 r0, r1;
;                     r0[0] = bflo(a.x) * fast_rcp(bflo(b.x)); r0[1] = bfhi(a.x) * fast_rcp(bfhi(b.x)); r0[2] = bflo(a.y) * fast_rcp(bflo(b.y)); r0[3] = bfhi(a.y) * fast_rcp(bfhi(b.y));
;                     r1[0] = bflo(a.z) * fast_rcp(bflo(b.z)); r1[1] = bfhi(a.z) * fast_rcp(bfhi(b.z)); r1[2] = bflo(a.w) * fast_rcp(bflo(b.w)); r1[3] = bfhi(a.w) * fast_rcp(bfhi(b.w));
;                     acc[ai][bj][m][0] *= r0; acc[ai][bj][m][1] *= r1; }
	v_lshlrev_b32_e32 v0, 16, v144
	v_pk_mul_f32 v[24:25], v[24:25], v[2:3]
	v_rcp_f32_e32 v2, v0
	v_and_b32_e32 v0, 0xffff0000, v144
	v_rcp_f32_e32 v3, v0
	v_lshlrev_b32_e32 v0, 16, v145
	v_rcp_f32_e32 v144, v0
	v_and_b32_e32 v0, 0xffff0000, v145
	v_rcp_f32_e32 v145, v0
	v_pk_mul_f32 v[26:27], v[26:27], v[148:149]
	v_lshlrev_b32_e32 v148, 16, v140
	v_and_b32_e32 v149, 0xffff0000, v140
	v_lshlrev_b32_e32 v140, 16, v141
	v_and_b32_e32 v141, 0xffff0000, v141
	v_lshlrev_b32_e32 v0, 16, v146
	v_pk_mul_f32 v[140:141], v[144:145], v[140:141]
	v_rcp_f32_e32 v144, v0
	v_and_b32_e32 v0, 0xffff0000, v146
	v_rcp_f32_e32 v145, v0
	v_lshlrev_b32_e32 v0, 16, v147
	v_rcp_f32_e32 v146, v0
	v_and_b32_e32 v0, 0xffff0000, v147
	v_pk_mul_f32 v[2:3], v[2:3], v[148:149]
	v_rcp_f32_e32 v147, v0
	s_waitcnt vmcnt(0)
	v_lshlrev_b32_e32 v0, 16, v136
	v_pk_mul_f32 v[16:17], v[16:17], v[2:3]
	v_rcp_f32_e32 v2, v0
	v_and_b32_e32 v0, 0xffff0000, v136
	v_rcp_f32_e32 v3, v0
	v_lshlrev_b32_e32 v0, 16, v137
	v_rcp_f32_e32 v136, v0
	v_and_b32_e32 v0, 0xffff0000, v137
	v_rcp_f32_e32 v137, v0
	v_pk_mul_f32 v[18:19], v[18:19], v[140:141]
	v_lshlrev_b32_e32 v140, 16, v132
	v_and_b32_e32 v141, 0xffff0000, v132
	v_lshlrev_b32_e32 v132, 16, v133
	v_and_b32_e32 v133, 0xffff0000, v133
	v_lshlrev_b32_e32 v0, 16, v138
	v_pk_mul_f32 v[132:133], v[136:137], v[132:133]
	v_rcp_f32_e32 v136, v0
	v_and_b32_e32 v0, 0xffff0000, v138
	v_rcp_f32_e32 v137, v0
	v_lshlrev_b32_e32 v0, 16, v139
	v_rcp_f32_e32 v138, v0
	v_and_b32_e32 v0, 0xffff0000, v139
	v_rcp_f32_e32 v139, v0
	v_lshlrev_b32_e32 v178, 16, v187
	v_and_b32_e32 v179, 0xffff0000, v187
	v_lshlrev_b32_e32 v170, 16, v171
	v_and_b32_e32 v171, 0xffff0000, v171
	v_lshlrev_b32_e32 v164, 16, v158
	v_and_b32_e32 v165, 0xffff0000, v158
	v_lshlrev_b32_e32 v158, 16, v159
	v_and_b32_e32 v159, 0xffff0000, v159
	v_lshlrev_b32_e32 v156, 16, v150
	v_and_b32_e32 v157, 0xffff0000, v150
	v_lshlrev_b32_e32 v150, 16, v151
	v_and_b32_e32 v151, 0xffff0000, v151
	v_lshlrev_b32_e32 v148, 16, v142
	v_and_b32_e32 v149, 0xffff0000, v142
	v_lshlrev_b32_e32 v142, 16, v143
	v_and_b32_e32 v143, 0xffff0000, v143
	v_pk_mul_f32 v[2:3], v[2:3], v[140:141]
	v_lshlrev_b32_e32 v140, 16, v134
	v_and_b32_e32 v141, 0xffff0000, v134
	v_lshlrev_b32_e32 v134, 16, v135
	v_and_b32_e32 v135, 0xffff0000, v135
	v_pk_mul_f32 v[180:181], v[180:181], v[240:241]
	v_pk_mul_f32 v[176:177], v[176:177], v[178:179]
	v_pk_mul_f32 v[168:169], v[168:169], v[170:171]
	v_pk_mul_f32 v[160:161], v[160:161], v[164:165]
	v_pk_mul_f32 v[158:159], v[162:163], v[158:159]
	v_pk_mul_f32 v[152:153], v[152:153], v[156:157]
	v_pk_mul_f32 v[150:151], v[154:155], v[150:151]
	v_pk_mul_f32 v[144:145], v[144:145], v[148:149]
	v_pk_mul_f32 v[142:143], v[146:147], v[142:143]
	v_pk_mul_f32 v[136:137], v[136:137], v[140:141]
	v_pk_mul_f32 v[134:135], v[138:139], v[134:135]
	v_pk_mul_f32 v[60:61], v[60:61], v[180:181]
	v_pk_mul_f32 v[46:47], v[46:47], v[176:177]
	v_pk_mul_f32 v[38:39], v[38:39], v[168:169]
	v_pk_mul_f32 v[36:37], v[36:37], v[166:167]
	v_pk_mul_f32 v[30:31], v[30:31], v[158:159]
	v_pk_mul_f32 v[28:29], v[28:29], v[160:161]
	v_pk_mul_f32 v[22:23], v[22:23], v[150:151]
	v_pk_mul_f32 v[20:21], v[20:21], v[152:153]
	v_pk_mul_f32 v[14:15], v[14:15], v[142:143]
	v_pk_mul_f32 v[12:13], v[12:13], v[144:145]
	v_pk_mul_f32 v[10:11], v[10:11], v[132:133]
	v_pk_mul_f32 v[8:9], v[8:9], v[2:3]
	v_pk_mul_f32 v[6:7], v[6:7], v[134:135]
	v_pk_mul_f32 v[4:5], v[4:5], v[136:137]
	s_branch .LBB0_263

; #define GAS __attribute__((address_space(1)))
; DI unsigned pk2(float lo, float hi) { f32x2 v = {lo, hi}; bf16x2_t b = __builtin_convertvector(v, bf16x2_t); return __builtin_bit_cast(unsigned, b); }
; DI float bflo(unsigned u) { return __uint_as_float(u << 16); }
; DI float bfhi(unsigned u) { return __uint_as_float(u & 0xffff0000u); }
;     __device__ __forceinline__ void operator()(const f32x4 (&acc)[2][2][4][2], const Unit& u, int wr, int wc, int fr, int fq) const {
;         const int row0 = u.pm * BM + wr * 64 + fr; const int col0 = u.pn * BM + wc * 32 + 8 * fq;
;         const int kg = u.ks >= 0 ? u.ks : 3;
; #pragma unroll
;         for (int ai = 0; ai < 2; ++ai) {
;             u32x4 ga[4][2];
; #pragma unroll
;             for (int m = 0; m < 4; ++m) { const bf16_t* gp = Gp + (size_t)(row0 + ai * HALF + m * 16) * GW + kg * DM + col0;
; #pragma unroll
;                 for (int bj = 0; bj < 2; ++bj) ga[m][bj] = *(const GAS u32x4*)(gp + bj * HALF); }
; #pragma unroll
;             for (int m = 0; m < 4; ++m) { bf16_t* rowp = O + (size_t)(row0 + ai * HALF + m * 16) * DM + col0;
;                 float* prow = part + ((size_t)(u.ks >= 0 ? u.ks : 0) * NCTX + (size_t)(row0 + ai * HALF + m * 16 - NLAT)) * DM + col0;
; #pragma unroll
;                 for (int bj = 0; bj < 2; ++bj) { const u32x4 a = ga[m][bj]; const f32x4 v0 = acc[ai][bj][m][0], v1 = acc[ai][bj][m][1];
;                     const f32x4 s0 = {v0[0] * bflo(a.x), v0[1] * bfhi(a.x), v0[2] * bflo(a.y), v0[3] * bfhi(a.y)}, s1 = {v1[0] * bflo(a.z), v1[1] * bfhi(a.z), v1[2] * bflo(a.w), v1[3] * bfhi(a.w)};
;                     if (u.ks >= 0) { *(GAS f32x4*)(prow + bj * HALF) = s0; *(GAS f32x4*)(prow + bj * HALF + 4) = s1; }
;                     else { u32x4 w; w.x = pk2(s0[0], s0[1]); w.y = pk2(s0[2], s0[3]); w.z = pk2(s1[0], s1[1]); w.w = pk2(s1[2], s1[3]);
;                         *(GAS u32x4*)(rowp + bj * HALF) = w; } } }
.LBB0_268:
	s_lshl_b32 s5, s4, 11
	s_and_b64 s[30:31], s[28:29], exec
	s_cselect_b32 s36, s5, 0x1800
	s_lshl_b64 s[30:31], s[36:37], 1
	v_ashrrev_i32_e32 v223, 31, v222
	s_add_u32 s30, s88, s30
	s_addc_u32 s31, s89, s31
	v_lshlrev_b64 v[166:167], 1, v[222:223]
	v_ashrrev_i32_e32 v225, 31, v224
	v_lshl_add_u64 v[2:3], s[30:31], 0, v[166:167]
	v_lshlrev_b64 v[132:133], 14, v[224:225]
	v_or_b32_e32 v164, 16, v224
	v_lshl_add_u64 v[132:133], v[2:3], 0, v[132:133]
	v_ashrrev_i32_e32 v165, 31, v164
	global_load_dwordx4 v[168:171], v[132:133], off nt
	global_load_dwordx4 v[156:159], v[132:133], off offset:256 nt
	v_lshlrev_b64 v[132:133], 14, v[164:165]
	v_or_b32_e32 v162, 32, v224
	v_lshl_add_u64 v[132:133], v[2:3], 0, v[132:133]
	v_ashrrev_i32_e32 v163, 31, v162
	global_load_dwordx4 v[152:155], v[132:133], off nt
	global_load_dwordx4 v[148:151], v[132:133], off offset:256 nt
	v_lshlrev_b64 v[132:133], 14, v[162:163]
	v_or_b32_e32 v160, 48, v224
	v_lshl_add_u64 v[132:133], v[2:3], 0, v[132:133]
	v_ashrrev_i32_e32 v161, 31, v160
	global_load_dwordx4 v[144:147], v[132:133], off nt
	global_load_dwordx4 v[140:143], v[132:133], off offset:256 nt
	v_lshlrev_b64 v[132:133], 14, v[160:161]
	v_lshl_add_u64 v[132:133], v[2:3], 0, v[132:133]
	global_load_dwordx4 v[136:139], v[132:133], off nt
	s_nop 0
	global_load_dwordx4 v[132:135], v[132:133], off offset:256 nt
	v_lshlrev_b64 v[172:173], 12, v[224:225]
	v_lshl_add_u64 v[172:173], s[10:11], 0, v[172:173]
	v_lshl_add_u64 v[166:167], v[172:173], 0, v[166:167]
	s_mov_b32 s5, s37
	s_lshl_b64 s[4:5], s[4:5], 10
	s_and_b64 s[28:29], s[28:29], exec
	s_cselect_b32 s29, s5, 0
	s_cselect_b32 s28, s4, 0
	s_mov_b64 s[4:5], -1
	s_and_b64 vcc, exec, s[26:27]
	s_waitcnt vmcnt(0)
	v_lshlrev_b32_e32 v172, 16, v168
	v_and_b32_e32 v173, 0xffff0000, v168
	v_lshlrev_b32_e32 v168, 16, v169
	v_and_b32_e32 v169, 0xffff0000, v169
	v_pk_mul_f32 v[130:131], v[130:131], v[168:169]
	v_lshlrev_b32_e32 v168, 16, v170
	v_and_b32_e32 v169, 0xffff0000, v170
	v_pk_mul_f32 v[124:125], v[124:125], v[168:169]
	v_lshlrev_b32_e32 v168, 16, v171
	v_and_b32_e32 v169, 0xffff0000, v171
	v_pk_mul_f32 v[128:129], v[128:129], v[172:173]
	v_pk_mul_f32 v[126:127], v[126:127], v[168:169]
	s_cbranch_vccz .LBB0_270
	v_cvt_pk_bf16_f32 v168, v128, v129
	v_cvt_pk_bf16_f32 v169, v130, v131
	v_cvt_pk_bf16_f32 v170, v124, v125
	v_cvt_pk_bf16_f32 v171, v126, v127
	global_store_dwordx4 v[166:167], v[168:171], off
	s_mov_b64 s[4:5], 0

; #define GAS __attribute__((address_space(1)))
; DI unsigned pk2(float lo, float hi) { f32x2 v = {lo, hi}; bf16x2_t b = __builtin_convertvector(v, bf16x2_t); return __builtin_bit_cast(unsigned, b); }
; DI float bflo(unsigned u) { return __uint_as_float(u << 16); }
; DI float bfhi(unsigned u) { return __uint_as_float(u & 0xffff0000u); }
;     __device__ __forceinline__ void operator()(const f32x4 (&acc)[2][2][4][2], const Unit& u, int wr, int wc, int fr, int fq) const {
;     ...
;         for (int ai = 0; ai < 2; ++ai) {
;             u32x4 ga[4][2];
; #pragma unroll
;             for (int m = 0; m < 4; ++m) { const bf16_t* gp = Gp + (size_t)(row0 + ai * HALF + m * 16) * GW + kg * DM + col0;
; #pragma unroll
;                 for (int bj = 0; bj < 2; ++bj) ga[m][bj] = *(const GAS u32x4*)(gp + bj * HALF); }
; #pragma unroll
;             for (int m = 0; m < 4; ++m) { bf16_t* rowp = O + (size_t)(row0 + ai * HALF + m * 16) * DM + col0;
;                 float* prow = part + ((size_t)(u.ks >= 0 ? u.ks : 0) * NCTX + (size_t)(row0 + ai * HALF + m * 16 - NLAT)) * DM + col0;
; #pragma unroll
;                 for (int bj = 0; bj < 2; ++bj) { const u32x4 a = ga[m][bj]; const f32x4 v0 = acc[ai][bj][m][0], v1 = acc[ai][bj][m][1];
;                     const f32x4 s0 = {v0[0] * bflo(a.x), v0[1] * bfhi(a.x), v0[2] * bflo(a.y), v0[3] * bfhi(a.y)}, s1 = {v1[0] * bflo(a.z), v1[1] * bfhi(a.z), v1[2] * bflo(a.w), v1[3] * bfhi(a.w)};
;                     if (u.ks >= 0) { *(GAS f32x4*)(prow + bj * HALF) = s0; *(GAS f32x4*)(prow + bj * HALF + 4) = s1; }
;                     else { u32x4 w; w.x = pk2(s0[0], s0[1]); w.y = pk2(s0[2], s0[3]); w.z = pk2(s1[0], s1[1]); w.w = pk2(s1[2], s1[3]);
;                         *(GAS u32x4*)(rowp + bj * HALF) = w; } } }
.LBB0_300:
	v_add_u32_e32 v106, 0x80, v224
	v_ashrrev_i32_e32 v107, 31, v106
	v_lshlrev_b64 v[68:69], 14, v[106:107]
	v_add_u32_e32 v100, 0x90, v224
	v_lshl_add_u64 v[68:69], v[2:3], 0, v[68:69]
	v_ashrrev_i32_e32 v101, 31, v100
	global_load_dwordx4 v[102:105], v[68:69], off nt
	global_load_dwordx4 v[92:95], v[68:69], off offset:256 nt
	v_lshlrev_b64 v[68:69], 14, v[100:101]
	v_add_u32_e32 v98, 0xa0, v224
	v_lshl_add_u64 v[68:69], v[2:3], 0, v[68:69]
	v_ashrrev_i32_e32 v99, 31, v98
	global_load_dwordx4 v[88:91], v[68:69], off nt
	global_load_dwordx4 v[84:87], v[68:69], off offset:256 nt
	v_lshlrev_b64 v[68:69], 14, v[98:99]
	v_add_u32_e32 v96, 0xb0, v224
	v_lshl_add_u64 v[68:69], v[2:3], 0, v[68:69]
	v_ashrrev_i32_e32 v97, 31, v96
	global_load_dwordx4 v[80:83], v[68:69], off nt
	global_load_dwordx4 v[76:79], v[68:69], off offset:256 nt
	v_lshlrev_b64 v[68:69], 14, v[96:97]
	v_lshl_add_u64 v[2:3], v[2:3], 0, v[68:69]
	global_load_dwordx4 v[72:75], v[2:3], off nt
	global_load_dwordx4 v[68:71], v[2:3], off offset:256 nt
	v_lshlrev_b64 v[2:3], 12, v[106:107]
	v_lshl_add_u64 v[2:3], s[10:11], 0, v[2:3]
	v_lshl_add_u64 v[2:3], v[222:223], 1, v[2:3]
	s_mov_b64 s[26:27], -1
	s_and_b64 vcc, exec, s[4:5]
	s_waitcnt vmcnt(7)
	v_lshlrev_b32_e32 v106, 16, v102
	v_and_b32_e32 v107, 0xffff0000, v102
	v_lshlrev_b32_e32 v102, 16, v103
	v_and_b32_e32 v103, 0xffff0000, v103
	v_pk_mul_f32 v[66:67], v[66:67], v[102:103]
	v_lshlrev_b32_e32 v102, 16, v104
	v_and_b32_e32 v103, 0xffff0000, v104
	v_pk_mul_f32 v[60:61], v[60:61], v[102:103]
	v_lshlrev_b32_e32 v102, 16, v105
	v_and_b32_e32 v103, 0xffff0000, v105
	v_pk_mul_f32 v[64:65], v[64:65], v[106:107]
	v_pk_mul_f32 v[62:63], v[62:63], v[102:103]
	s_cbranch_vccnz .LBB0_302
	v_cvt_pk_bf16_f32 v102, v64, v65
	v_cvt_pk_bf16_f32 v103, v66, v67
	v_cvt_pk_bf16_f32 v104, v60, v61
	v_cvt_pk_bf16_f32 v105, v62, v63
	s_mov_b64 s[26:27], 0
	global_store_dwordx4 v[2:3], v[102:105], off
